# c14 + fused-LN epilogues (out-proj, down): the 8 row-statistics slot loads issued as one batch instead of one L2 round trip each
# baseline (speedup 1.0000x reference)
;     __device__ __forceinline__ void fused(AccT& acc, const Unit& u, int wr, int wc, int fr_in, int fq_in, LAS unsigned char* lds, int wid, int lane_in) const {
;     ...
;         if (lane < 32) {
;             const unsigned long long* slot = xbuf + (size_t)(u.pm * BM + row) * 8; float mt[8], m2[8]; float ms = 0.f;
; #pragma unroll
;             for (int t = 0; t < 8; ++t) { const unsigned long long w = __hip_atomic_load(slot + t, __ATOMIC_RELAXED, __HIP_MEMORY_SCOPE_AGENT); mt[t] = __uint_as_float((unsigned)w); m2[t] = __uint_as_float((unsigned)(w >> 32)); ms += mt[t]; }
;             const float mean = ms * 0.125f; float q = 0.f;
; #pragma unroll
;             for (int t = 0; t < 8; ++t) { const float dm = mt[t] - mean; q += m2[t] + 256.0f * dm * dm; }
;             S[row] = (f32x2){mean, rsqrtf(q * (1.0f / 2048.0f) + LN_EPS)};
.LBB0_1087:
	s_waitcnt vmcnt(0) lgkmcnt(0)
	s_barrier
	s_and_saveexec_b64 s[16:17], s[38:39]
	s_cbranch_execz .LBB0_1089
	v_readlane_b32 s0, v253, 9
	v_lshlrev_b64 v[164:165], 6, v[164:165]
	v_readlane_b32 s1, v253, 10
	v_lshl_add_u32 v1, v1, 3, 0
	s_nop 0
	v_lshl_add_u64 v[164:165], s[0:1], 0, v[164:165]
	global_load_dwordx2 v[166:167], v[164:165], off sc1
	global_load_dwordx2 v[168:169], v[164:165], off offset:8 sc1
	global_load_dwordx2 v[170:171], v[164:165], off offset:16 sc1
	global_load_dwordx2 v[172:173], v[164:165], off offset:24 sc1
	global_load_dwordx2 v[174:175], v[164:165], off offset:32 sc1
	global_load_dwordx2 v[176:177], v[164:165], off offset:40 sc1
	global_load_dwordx2 v[178:179], v[164:165], off offset:48 sc1
	global_load_dwordx2 v[164:165], v[164:165], off offset:56 sc1
	s_waitcnt vmcnt(0)
	v_add_f32_e32 v180, 0, v166
	v_add_f32_e32 v180, v180, v168
	v_add_f32_e32 v180, v180, v170
	v_add_f32_e32 v180, v180, v172
	v_add_f32_e32 v180, v180, v174
	v_add_f32_e32 v180, v180, v176
	v_add_f32_e32 v180, v180, v178
	v_add_f32_e32 v181, v180, v164
	v_fmamk_f32 v166, v181, 0xbe000000, v166
	v_mul_f32_e32 v182, 0x43800000, v166
	v_fmac_f32_e32 v167, v166, v182
	v_add_f32_e32 v166, 0, v167
	v_fmamk_f32 v167, v181, 0xbe000000, v168
	v_mul_f32_e32 v168, 0x43800000, v167
	v_fmac_f32_e32 v169, v167, v168
	v_fmamk_f32 v167, v181, 0xbe000000, v170
	v_mul_f32_e32 v168, 0x43800000, v167
	v_fmac_f32_e32 v171, v167, v168
	v_fmamk_f32 v167, v181, 0xbe000000, v172
	v_mul_f32_e32 v168, 0x43800000, v167
	v_fmac_f32_e32 v173, v167, v168
	v_fmamk_f32 v167, v181, 0xbe000000, v174
	v_mul_f32_e32 v168, 0x43800000, v167
	v_add_f32_e32 v166, v169, v166
	v_fmac_f32_e32 v175, v167, v168
	v_fmamk_f32 v167, v181, 0xbe000000, v176
	v_add_f32_e32 v166, v171, v166
	v_mul_f32_e32 v168, 0x43800000, v167
	v_add_f32_e32 v166, v173, v166
	v_fmac_f32_e32 v177, v167, v168
	v_fmamk_f32 v167, v181, 0xbe000000, v178
	v_add_f32_e32 v166, v175, v166
	v_mul_f32_e32 v168, 0x43800000, v167
	v_fmamk_f32 v164, v181, 0xbe000000, v164
	v_add_f32_e32 v166, v177, v166
	v_fmac_f32_e32 v179, v167, v168
	v_mul_f32_e32 v167, 0x43800000, v164
	v_add_f32_e32 v166, v179, v166
	v_fmac_f32_e32 v165, v164, v167
	v_add_f32_e32 v164, v165, v166
	v_fmamk_f32 v164, v164, 0x3a000000, v226
	v_cmp_gt_f32_e32 vcc, s15, v164
	v_mul_f32_e32 v165, 0x4b800000, v164
	v_mul_f32_e32 v180, 0x3e000000, v181
	v_cndmask_b32_e32 v164, v164, v165, vcc
	v_rsq_f32_e32 v164, v164
	s_nop 0
	v_mul_f32_e32 v165, 0x45800000, v164
	v_cndmask_b32_e32 v181, v164, v165, vcc
	ds_write_b64 v1, v[180:181] offset:8192
